# v110 + in-proj/up epilogues: per-row sum-of-squares loads issued at the unit header (hidden under the previous store drain) instead of at epilogue start
# speedup vs baseline: 1.0028x; 1.0004x over previous
.LBB0_129:
	v_lshl_add_u32 v152, s60, 8, v145
	v_ashrrev_i32_e32 v153, 31, v152
	v_lshl_add_u64 v[154:155], v[152:153], 2, s[6:7]
	global_load_dword v241, v[154:155], off
	global_load_dword v242, v[154:155], off offset:64
	global_load_dword v243, v[154:155], off offset:128
	global_load_dword v244, v[154:155], off offset:192
	global_load_dword v245, v[154:155], off offset:512
	global_load_dword v246, v[154:155], off offset:576
	global_load_dword v247, v[154:155], off offset:640
	global_load_dword v248, v[154:155], off offset:704
	s_add_i32 s56, s56, 1
	v_readlane_b32 s23, v254, 56
	v_readlane_b32 s26, v252, 7
	s_mul_i32 s23, s56, s23
	s_mul_hi_u32 s25, s56, s26
	s_add_i32 s25, s25, s23
	s_mul_i32 s23, s56, s26
	v_readlane_b32 s26, v252, 0
	s_add_u32 s26, s23, s26
	v_readlane_b32 s23, v254, 17
	s_addc_u32 s27, s25, s23
	v_mov_b64_e32 v[2:3], 0xbc0
	v_cmp_lt_i64_e64 s[44:45], s[26:27], v[2:3]
	v_mov_b64_e32 v[2:3], 0xbbf
	v_cmp_gt_i64_e32 vcc, s[26:27], v[2:3]
	s_cbranch_vccnz .LBB0_131
	s_ashr_i32 s22, s26, 31
	s_lshr_b32 s22, s22, 29
	s_add_i32 s22, s26, s22
	s_ashr_i32 s23, s22, 3
	s_and_b32 s22, s22, -8
	s_sub_i32 s22, s26, s22
	s_cmp_lt_i32 s22, 0
	s_movk_i32 s24, 0x179
	s_cselect_b32 s24, s24, 0x178
	s_mul_i32 s22, s22, s24
	s_add_i32 s22, s22, s23
	s_mul_hi_i32 s23, s22, 0xae4c415d
	s_add_i32 s23, s23, s22
	s_lshr_b32 s24, s23, 31
	s_ashr_i32 s23, s23, 7
	s_add_i32 s23, s23, s24
	s_lshl_b32 s24, s23, 2
	s_sub_i32 s25, 64, s24
	s_min_i32 s25, s25, 4
	s_abs_i32 s26, s25
	v_cvt_f32_u32_e32 v2, s26
	s_sub_i32 s28, 0, s26
	s_mulk_i32 s23, 0xbc
	s_sub_i32 s23, s22, s23
	v_rcp_iflag_f32_e32 v2, v2
	s_abs_i32 s22, s23
	s_xor_b32 s27, s23, s25
	s_ashr_i32 s27, s27, 31
	v_mul_f32_e32 v2, 0x4f7ffffe, v2
	v_cvt_u32_f32_e32 v2, v2
	s_nop 0
	v_readfirstlane_b32 s29, v2
	s_mul_i32 s28, s28, s29
	s_mul_hi_u32 s28, s29, s28
	s_add_i32 s29, s29, s28
	s_mul_hi_u32 s28, s22, s29
	s_mul_i32 s29, s28, s26
	s_sub_i32 s22, s22, s29
	s_add_i32 s40, s28, 1
	s_sub_i32 s29, s22, s26
	s_cmp_ge_u32 s22, s26
	s_cselect_b32 s28, s40, s28
	s_cselect_b32 s22, s29, s22
	s_add_i32 s29, s28, 1
	s_cmp_ge_u32 s22, s26
	s_cselect_b32 s22, s29, s28
	s_xor_b32 s22, s22, s27
	s_sub_i32 s22, s22, s27
	s_mul_i32 s25, s22, s25
	s_sub_i32 s23, s23, s25
	s_add_i32 s24, s24, s23

.LBB0_135:
	v_lshl_add_u32 v152, s60, 8, v145
	v_ashrrev_i32_e32 v153, 31, v152
	v_lshl_add_u64 v[154:155], v[152:153], 2, s[6:7]
	v_mov_b32_e32 v144, v241
	v_mov_b32_e32 v146, v242
	v_mov_b32_e32 v148, v243
	v_mov_b32_e32 v150, v244
	v_mov_b32_e32 v156, v245
	v_mov_b32_e32 v157, v246
	v_mov_b32_e32 v158, v247
	s_nop 0
	v_mov_b32_e32 v154, v248
	s_add_i32 s23, s59, -4
	s_cmp_gt_u32 s23, 11
	s_waitcnt vmcnt(0)
	v_fmamk_f32 v144, v144, 0x39800000, v1
	v_fmamk_f32 v146, v146, 0x39800000, v1
	v_fmamk_f32 v148, v148, 0x39800000, v1
	v_fmamk_f32 v150, v150, 0x39800000, v1
	v_fmamk_f32 v155, v156, 0x39800000, v1
	v_fmamk_f32 v157, v157, 0x39800000, v1
	v_fmamk_f32 v159, v158, 0x39800000, v1
	v_fmamk_f32 v161, v154, 0x39800000, v1
	v_rsq_f32_e32 v160, v144
	v_rsq_f32_e32 v158, v146
	v_rsq_f32_e32 v156, v148
	v_rsq_f32_e32 v154, v150
	v_rsq_f32_e32 v150, v155
	v_rsq_f32_e32 v148, v157
	v_rsq_f32_e32 v146, v159
	v_rsq_f32_e32 v144, v161
	s_cbranch_scc0 .LBB0_138
	s_cmp_eq_u32 s59, 46
	s_mov_b64 s[34:35], -1
	s_cbranch_scc0 .LBB0_149

.LBB0_1021:
	v_lshl_add_u32 v226, s78, 8, v243
	v_ashrrev_i32_e32 v227, 31, v226
	v_lshl_add_u64 v[62:63], v[226:227], 2, s[12:13]
	global_load_dword v228, v[62:63], off
	global_load_dword v236, v[62:63], off offset:64
	global_load_dword v234, v[62:63], off offset:128
	global_load_dword v230, v[62:63], off offset:192
	global_load_dword v212, v[62:63], off offset:512
	global_load_dword v227, v[62:63], off offset:576
	global_load_dword v213, v[62:63], off offset:640
	global_load_dword v238, v[62:63], off offset:704
	s_add_i32 s76, s76, 1
	v_readlane_b32 s30, v254, 56
	v_readlane_b32 s45, v252, 7
	s_mul_i32 s30, s76, s30
	s_mul_hi_u32 s44, s76, s45
	s_add_i32 s44, s44, s30
	s_mul_i32 s30, s76, s45
	v_readlane_b32 s45, v252, 0
	s_add_u32 s54, s30, s45
	v_readlane_b32 s30, v254, 17
	s_addc_u32 s55, s44, s30
	v_mov_b64_e32 v[2:3], 0x1580
	v_cmp_lt_i64_e64 s[44:45], s[54:55], v[2:3]
	v_mov_b64_e32 v[2:3], 0x157f
	v_cmp_gt_i64_e32 vcc, s[54:55], v[2:3]
	s_cbranch_vccnz .LBB0_1023
	s_ashr_i32 s30, s54, 31
	s_lshr_b32 s30, s30, 29
	s_add_i32 s30, s54, s30
	s_ashr_i32 s50, s30, 3
	s_and_b32 s30, s30, -8
	s_sub_i32 s30, s54, s30
	s_cmp_lt_i32 s30, 0
	s_movk_i32 s51, 0x2b1
	s_cselect_b32 s51, s51, 0x2b0
	s_mul_i32 s30, s30, s51
	s_add_i32 s30, s30, s50
	s_mul_hi_i32 s50, s30, 0x2fa0be83
	s_lshr_b32 s51, s50, 31
	s_ashr_i32 s50, s50, 7
	s_add_i32 s50, s50, s51
	s_lshl_b32 s51, s50, 3
	s_sub_i32 s52, 64, s51
	s_min_i32 s52, s52, 8
	s_abs_i32 s53, s52
	v_cvt_f32_u32_e32 v2, s53
	s_sub_i32 s55, 0, s53
	s_mulk_i32 s50, 0x2b0
	s_sub_i32 s30, s30, s50
	v_rcp_iflag_f32_e32 v2, v2
	s_abs_i32 s50, s30
	s_xor_b32 s54, s30, s52
	s_ashr_i32 s54, s54, 31
	v_mul_f32_e32 v2, 0x4f7ffffe, v2
	v_cvt_u32_f32_e32 v2, v2
	s_nop 0
	v_readfirstlane_b32 s56, v2
	s_mul_i32 s55, s55, s56
	s_mul_hi_u32 s55, s56, s55
	s_add_i32 s56, s56, s55
	s_mul_hi_u32 s55, s50, s56
	s_mul_i32 s56, s55, s53
	s_sub_i32 s50, s50, s56
	s_add_i32 s57, s55, 1
	s_sub_i32 s56, s50, s53
	s_cmp_ge_u32 s50, s53
	s_cselect_b32 s55, s57, s55
	s_cselect_b32 s50, s56, s50
	s_add_i32 s56, s55, 1
	s_cmp_ge_u32 s50, s53
	s_cselect_b32 s50, s56, s55
	s_xor_b32 s50, s50, s54
	s_sub_i32 s50, s50, s54
	s_mul_i32 s52, s50, s52
	s_sub_i32 s30, s30, s52
	s_add_i32 s52, s51, s30

.LBB0_1027:
	v_lshl_add_u32 v226, s78, 8, v243
	v_lshl_or_b32 v232, s77, 7, v245
	v_ashrrev_i32_e32 v233, 31, v232
	v_mov_b32_e32 v199, v228
	v_mov_b32_e32 v180, v230
	v_mov_b32_e32 v181, v238
	v_lshlrev_b64 v[62:63], 2, v[232:233]
	v_mov_b32_e32 v196, v241
	v_mov_b32_e32 v198, v242
	v_lshl_add_u64 v[64:65], s[8:9], 0, v[62:63]
	global_load_dwordx4 v[74:77], v[64:65], off offset:16
	global_load_dwordx4 v[90:93], v[64:65], off
	v_lshl_add_u64 v[64:65], s[28:29], 0, v[62:63]
	global_load_dwordx4 v[66:69], v[64:65], off offset:16
	global_load_dwordx4 v[102:105], v[64:65], off
	v_lshl_add_u64 v[64:65], s[34:35], 0, v[62:63]
	global_load_dwordx4 v[78:81], v[64:65], off offset:16
	global_load_dwordx4 v[94:97], v[64:65], off
	v_lshl_add_u64 v[64:65], s[36:37], 0, v[62:63]
	global_load_dwordx4 v[70:73], v[64:65], off offset:16
	global_load_dwordx4 v[106:109], v[64:65], off
	v_lshl_add_u64 v[64:65], s[40:41], 0, v[62:63]
	v_lshl_add_u64 v[110:111], s[48:49], 0, v[62:63]
	global_load_dwordx4 v[82:85], v[64:65], off offset:16
	global_load_dwordx4 v[98:101], v[64:65], off
	s_nop 0
	global_load_dwordx4 v[62:65], v[110:111], off offset:16
	s_nop 0
	global_load_dwordx4 v[110:113], v[110:111], off
	s_waitcnt vmcnt(0)
	v_fmamk_f32 v180, v180, 0x39800000, v1
	v_rsq_f32_e32 v230, v180
	v_cndmask_b32_e64 v180, 0, 1, s[4:5]
	v_cmp_ne_u32_e64 s[46:47], 1, v180
	v_fmamk_f32 v181, v181, 0x39800000, v1
	v_rsq_f32_e32 v228, v181
	s_and_saveexec_b64 s[2:3], s[42:43]
	s_cbranch_execz .LBB0_1030
	v_pk_mul_f32 v[182:183], v[128:129], v[230:231] op_sel_hi:[1,0]
	v_pk_mul_f32 v[180:181], v[126:127], v[230:231] op_sel_hi:[1,0]
	ds_write_b128 v246, v[180:183]
	v_pk_mul_f32 v[182:183], v[120:121], v[230:231] op_sel_hi:[1,0]
	v_pk_mul_f32 v[180:181], v[118:119], v[230:231] op_sel_hi:[1,0]
	ds_write_b128 v246, v[180:183] offset:16
	v_pk_mul_f32 v[182:183], v[124:125], v[230:231] op_sel_hi:[1,0]
	v_pk_mul_f32 v[180:181], v[122:123], v[230:231] op_sel_hi:[1,0]
	ds_write_b128 v246, v[180:183] offset:512
	v_pk_mul_f32 v[182:183], v[116:117], v[230:231] op_sel_hi:[1,0]
	v_pk_mul_f32 v[180:181], v[114:115], v[230:231] op_sel_hi:[1,0]
	ds_write_b128 v246, v[180:183] offset:528
	v_pk_mul_f32 v[182:183], v[16:17], v[228:229] op_sel_hi:[1,0]
	v_pk_mul_f32 v[180:181], v[14:15], v[228:229] op_sel_hi:[1,0]
	v_pk_mul_f32 v[186:187], v[8:9], v[228:229] op_sel_hi:[1,0]
	v_pk_mul_f32 v[184:185], v[6:7], v[228:229] op_sel_hi:[1,0]
	v_pk_mul_f32 v[190:191], v[12:13], v[228:229] op_sel_hi:[1,0]
	v_pk_mul_f32 v[188:189], v[10:11], v[228:229] op_sel_hi:[1,0]
	v_pk_mul_f32 v[194:195], v[4:5], v[228:229] op_sel_hi:[1,0]
	v_pk_mul_f32 v[192:193], v[2:3], v[228:229] op_sel_hi:[1,0]
	s_and_b64 vcc, exec, s[46:47]
	ds_write_b128 v247, v[180:183]
	ds_write_b128 v247, v[184:187] offset:16
	ds_write_b128 v246, v[188:191] offset:4608
	ds_write_b128 v246, v[192:195] offset:4624
	s_cbranch_vccnz .LBB0_1030
	s_mul_i32 s30, s78, 0x56
	s_add_i32 s58, s30, s77
	s_ashr_i32 s59, s58, 31
	s_lshl_b64 s[58:59], s[58:59], 12
	v_ashrrev_i32_e32 v197, 31, v196
	s_add_u32 s58, s71, s58
	v_lshlrev_b64 v[200:201], 10, v[196:197]
	s_addc_u32 s59, s72, s59
	v_lshl_add_u64 v[200:201], s[58:59], 0, v[200:201]
	s_lshl_b32 s30, s73, 2
	v_lshlrev_b32_e32 v202, 3, v198
	v_lshl_add_u64 v[200:201], v[200:201], 0, s[30:31]
	v_ashrrev_i32_e32 v203, 31, v202
	s_movk_i32 s58, 0xd000
	v_lshl_add_u64 v[200:201], v[202:203], 2, v[200:201]
	s_mov_b32 s59, -1
	v_lshl_add_u64 v[202:203], v[200:201], 0, s[58:59]
	v_add_co_u32_e32 v200, vcc, 0xffffd000, v200
	s_nop 1
	v_addc_co_u32_e32 v201, vcc, -1, v201, vcc
	global_store_dwordx4 v[200:201], v[180:183], off
	global_store_dwordx4 v[202:203], v[184:187], off offset:16
	global_store_dwordx4 v[202:203], v[188:191], off offset:512
	global_store_dwordx4 v[202:203], v[192:195], off offset:528
